# branch-B GEMM merge epilogue: tile loads batched (16 in flight, one wait) instead of eight serialized groups
# baseline (speedup 1.0000x reference)
; __device__ __forceinline__ float bf_lo(unsigned w) { return __uint_as_float(w << 16); }
; __device__ __forceinline__ float bf_hi(unsigned w) { return __uint_as_float(w & 0xffff0000u); }
; __device__ __forceinline__ u32x4 pack8(f32x4 a, f32x4 b) { u32x4 w; w.x = cvt_pk_bf16(a[0], a[1]); w.y = cvt_pk_bf16(a[2], a[3]); w.z = cvt_pk_bf16(b[0], b[1]); w.w = cvt_pk_bf16(b[2], b[3]); return w; }
;     __device__ __forceinline__ void operator()(const f32x4 (&acc)[2][2][4][2], const Unit& u, int wr, int wc, int fr, int fq) const {
;         const int row0 = u.pm * BM + wr * 64 + fr, c0 = u.pn * BM + wc * 32 + 8 * fq;
; #pragma unroll
;         for (int ai = 0; ai < 2; ++ai)
; #pragma unroll
;             for (int m = 0; m < 4; ++m) { const size_t off = (size_t)(row0 + ai * HALF + m * 16) * 2048 + c0;
; #pragma unroll
;                 for (int bj = 0; bj < 2; ++bj) { const u32x4 t = *(const u32x4*)(T + off + bj * HALF); const u32x4 g = *(const u32x4*)(G + off + bj * HALF);
;                     const f32x4 v0 = acc[ai][bj][m][0], v1 = acc[ai][bj][m][1];
;                     const f32x4 o0 = {bf_lo(t.x) + bf_lo(g.x) * v0[0], bf_hi(t.x) + bf_hi(g.x) * v0[1], bf_lo(t.y) + bf_lo(g.y) * v0[2], bf_hi(t.y) + bf_hi(g.y) * v0[3]};
;                     const f32x4 o1 = {bf_lo(t.z) + bf_lo(g.z) * v1[0], bf_hi(t.z) + bf_hi(g.z) * v1[1], bf_lo(t.w) + bf_lo(g.w) * v1[2], bf_hi(t.w) + bf_hi(g.w) * v1[3]};
;                     *(u32x4*)(T + off + bj * HALF) = pack8(o0, o1); } }
.LBB0_760:
	s_andn2_b64 vcc, exec, s[2:3]
	s_mov_b64 s[2:3], -1
	v_lshlrev_b32_e32 v144, 12, v150
	v_lshl_add_u32 v144, v152, 1, v144
	s_lshl_b32 s98, s34, 20
	s_lshl_b32 s99, s57, 9
	s_add_u32 s98, s98, s99
	s_add_u32 s100, s12, s98
	s_addc_u32 s101, s13, 0
	s_add_u32 s98, s10, s98
	s_addc_u32 s99, s11, 0
	global_load_dwordx4 v[160:163], v144, s[98:99]
	global_load_dwordx4 v[164:167], v144, s[100:101]
	global_load_dwordx4 v[168:171], v144, s[98:99] offset:256
	global_load_dwordx4 v[172:175], v144, s[100:101] offset:256
	s_add_u32 s98, s98, 0x10000
	s_addc_u32 s99, s99, 0
	s_add_u32 s100, s100, 0x10000
	s_addc_u32 s101, s101, 0
	global_load_dwordx4 v[176:179], v144, s[98:99]
	global_load_dwordx4 v[180:183], v144, s[100:101]
	global_load_dwordx4 v[184:187], v144, s[98:99] offset:256
	global_load_dwordx4 v[188:191], v144, s[100:101] offset:256
	s_add_u32 s98, s98, 0x10000
	s_addc_u32 s99, s99, 0
	s_add_u32 s100, s100, 0x10000
	s_addc_u32 s101, s101, 0
	global_load_dwordx4 v[192:195], v144, s[98:99]
	global_load_dwordx4 v[196:199], v144, s[100:101]
	global_load_dwordx4 v[200:203], v144, s[98:99] offset:256
	global_load_dwordx4 v[204:207], v144, s[100:101] offset:256
	s_add_u32 s98, s98, 0x10000
	s_addc_u32 s99, s99, 0
	s_add_u32 s100, s100, 0x10000
	s_addc_u32 s101, s101, 0
	global_load_dwordx4 v[208:211], v144, s[98:99]
	global_load_dwordx4 v[212:215], v144, s[100:101]
	global_load_dwordx4 v[216:219], v144, s[98:99] offset:256
	global_load_dwordx4 v[220:223], v144, s[100:101] offset:256
	s_waitcnt vmcnt(0)
	v_lshlrev_b32_e32 v224, 16, v160
	v_and_b32_e32 v225, 0xffff0000, v160
	v_lshlrev_b32_e32 v226, 16, v164
	v_and_b32_e32 v227, 0xffff0000, v164
	v_fmac_f32_e32 v224, v124, v226
	v_fmac_f32_e32 v225, v125, v227
	v_cvt_pk_bf16_f32 v160, v224, v225
	v_lshlrev_b32_e32 v228, 16, v161
	v_and_b32_e32 v229, 0xffff0000, v161
	v_lshlrev_b32_e32 v230, 16, v165
	v_and_b32_e32 v231, 0xffff0000, v165
	v_fmac_f32_e32 v228, v126, v230
	v_fmac_f32_e32 v229, v127, v231
	v_cvt_pk_bf16_f32 v161, v228, v229
	v_lshlrev_b32_e32 v224, 16, v162
	v_and_b32_e32 v225, 0xffff0000, v162
	v_lshlrev_b32_e32 v226, 16, v166
	v_and_b32_e32 v227, 0xffff0000, v166
	v_fmac_f32_e32 v224, v120, v226
	v_fmac_f32_e32 v225, v121, v227
	v_cvt_pk_bf16_f32 v162, v224, v225
	v_lshlrev_b32_e32 v228, 16, v163
	v_and_b32_e32 v229, 0xffff0000, v163
	v_lshlrev_b32_e32 v230, 16, v167
	v_and_b32_e32 v231, 0xffff0000, v167
	v_fmac_f32_e32 v228, v122, v230
	v_fmac_f32_e32 v229, v123, v231
	v_cvt_pk_bf16_f32 v163, v228, v229
	v_lshlrev_b32_e32 v224, 16, v168
	v_and_b32_e32 v225, 0xffff0000, v168
	v_lshlrev_b32_e32 v226, 16, v172
	v_and_b32_e32 v227, 0xffff0000, v172
	v_fmac_f32_e32 v224, v116, v226
	v_fmac_f32_e32 v225, v117, v227
	v_cvt_pk_bf16_f32 v168, v224, v225
	v_lshlrev_b32_e32 v228, 16, v169
	v_and_b32_e32 v229, 0xffff0000, v169
	v_lshlrev_b32_e32 v230, 16, v173
	v_and_b32_e32 v231, 0xffff0000, v173
	v_fmac_f32_e32 v228, v118, v230
	v_fmac_f32_e32 v229, v119, v231
	v_cvt_pk_bf16_f32 v169, v228, v229
	v_lshlrev_b32_e32 v224, 16, v170
	v_and_b32_e32 v225, 0xffff0000, v170
	v_lshlrev_b32_e32 v226, 16, v174
	v_and_b32_e32 v227, 0xffff0000, v174
	v_fmac_f32_e32 v224, v112, v226
	v_fmac_f32_e32 v225, v113, v227
	v_cvt_pk_bf16_f32 v170, v224, v225
	v_lshlrev_b32_e32 v228, 16, v171
	v_and_b32_e32 v229, 0xffff0000, v171
	v_lshlrev_b32_e32 v230, 16, v175
	v_and_b32_e32 v231, 0xffff0000, v175
	v_fmac_f32_e32 v228, v114, v230
	v_fmac_f32_e32 v229, v115, v231
	v_cvt_pk_bf16_f32 v171, v228, v229
	v_lshlrev_b32_e32 v224, 16, v176
	v_and_b32_e32 v225, 0xffff0000, v176
	v_lshlrev_b32_e32 v226, 16, v180
	v_and_b32_e32 v227, 0xffff0000, v180
	v_fmac_f32_e32 v224, v108, v226
	v_fmac_f32_e32 v225, v109, v227
	v_cvt_pk_bf16_f32 v176, v224, v225
	v_lshlrev_b32_e32 v228, 16, v177
	v_and_b32_e32 v229, 0xffff0000, v177
	v_lshlrev_b32_e32 v230, 16, v181
	v_and_b32_e32 v231, 0xffff0000, v181
	v_fmac_f32_e32 v228, v110, v230
	v_fmac_f32_e32 v229, v111, v231
	v_cvt_pk_bf16_f32 v177, v228, v229
	v_lshlrev_b32_e32 v224, 16, v178
	v_and_b32_e32 v225, 0xffff0000, v178
	v_lshlrev_b32_e32 v226, 16, v182
	v_and_b32_e32 v227, 0xffff0000, v182
	v_fmac_f32_e32 v224, v104, v226
	v_fmac_f32_e32 v225, v105, v227
	v_cvt_pk_bf16_f32 v178, v224, v225
	v_lshlrev_b32_e32 v228, 16, v179
	v_and_b32_e32 v229, 0xffff0000, v179
	v_lshlrev_b32_e32 v230, 16, v183
	v_and_b32_e32 v231, 0xffff0000, v183
	v_fmac_f32_e32 v228, v106, v230
	v_fmac_f32_e32 v229, v107, v231
	v_cvt_pk_bf16_f32 v179, v228, v229
	v_lshlrev_b32_e32 v224, 16, v184
	v_and_b32_e32 v225, 0xffff0000, v184
	v_lshlrev_b32_e32 v226, 16, v188
	v_and_b32_e32 v227, 0xffff0000, v188
	v_fmac_f32_e32 v224, v100, v226
	v_fmac_f32_e32 v225, v101, v227
	v_cvt_pk_bf16_f32 v184, v224, v225
	v_lshlrev_b32_e32 v228, 16, v185
	v_and_b32_e32 v229, 0xffff0000, v185
	v_lshlrev_b32_e32 v230, 16, v189
	v_and_b32_e32 v231, 0xffff0000, v189
	v_fmac_f32_e32 v228, v102, v230
	v_fmac_f32_e32 v229, v103, v231
	v_cvt_pk_bf16_f32 v185, v228, v229
	v_lshlrev_b32_e32 v224, 16, v186
	v_and_b32_e32 v225, 0xffff0000, v186
	v_lshlrev_b32_e32 v226, 16, v190
	v_and_b32_e32 v227, 0xffff0000, v190
	v_fmac_f32_e32 v224, v96, v226
	v_fmac_f32_e32 v225, v97, v227
	v_cvt_pk_bf16_f32 v186, v224, v225
	v_lshlrev_b32_e32 v228, 16, v187
	v_and_b32_e32 v229, 0xffff0000, v187
	v_lshlrev_b32_e32 v230, 16, v191
	v_and_b32_e32 v231, 0xffff0000, v191
	v_fmac_f32_e32 v228, v98, v230
	v_fmac_f32_e32 v229, v99, v231
	v_cvt_pk_bf16_f32 v187, v228, v229
	v_lshlrev_b32_e32 v224, 16, v192
	v_and_b32_e32 v225, 0xffff0000, v192
	v_lshlrev_b32_e32 v226, 16, v196
	v_and_b32_e32 v227, 0xffff0000, v196
	v_fmac_f32_e32 v224, v92, v226
; __device__ __forceinline__ float bf_lo(unsigned w) { return __uint_as_float(w << 16); }
; __device__ __forceinline__ float bf_hi(unsigned w) { return __uint_as_float(w & 0xffff0000u); }
; __device__ __forceinline__ u32x4 pack8(f32x4 a, f32x4 b) { u32x4 w; w.x = cvt_pk_bf16(a[0], a[1]); w.y = cvt_pk_bf16(a[2], a[3]); w.z = cvt_pk_bf16(b[0], b[1]); w.w = cvt_pk_bf16(b[2], b[3]); return w; }
;     __device__ __forceinline__ void operator()(const f32x4 (&acc)[2][2][4][2], const Unit& u, int wr, int wc, int fr, int fq) const {
;         const int row0 = u.pm * BM + wr * 64 + fr, c0 = u.pn * BM + wc * 32 + 8 * fq;
; #pragma unroll
;         for (int ai = 0; ai < 2; ++ai)
; #pragma unroll
;             for (int m = 0; m < 4; ++m) { const size_t off = (size_t)(row0 + ai * HALF + m * 16) * 2048 + c0;
; #pragma unroll
;                 for (int bj = 0; bj < 2; ++bj) { const u32x4 t = *(const u32x4*)(T + off + bj * HALF); const u32x4 g = *(const u32x4*)(G + off + bj * HALF);
;                     const f32x4 v0 = acc[ai][bj][m][0], v1 = acc[ai][bj][m][1];
;                     const f32x4 o0 = {bf_lo(t.x) + bf_lo(g.x) * v0[0], bf_hi(t.x) + bf_hi(g.x) * v0[1], bf_lo(t.y) + bf_lo(g.y) * v0[2], bf_hi(t.y) + bf_hi(g.y) * v0[3]};
;                     const f32x4 o1 = {bf_lo(t.z) + bf_lo(g.z) * v1[0], bf_hi(t.z) + bf_hi(g.z) * v1[1], bf_lo(t.w) + bf_lo(g.w) * v1[2], bf_hi(t.w) + bf_hi(g.w) * v1[3]};
;                     *(u32x4*)(T + off + bj * HALF) = pack8(o0, o1); } }
	v_fmac_f32_e32 v225, v93, v227
	v_cvt_pk_bf16_f32 v192, v224, v225
	v_lshlrev_b32_e32 v228, 16, v193
	v_and_b32_e32 v229, 0xffff0000, v193
	v_lshlrev_b32_e32 v230, 16, v197
	v_and_b32_e32 v231, 0xffff0000, v197
	v_fmac_f32_e32 v228, v94, v230
	v_fmac_f32_e32 v229, v95, v231
	v_cvt_pk_bf16_f32 v193, v228, v229
	v_lshlrev_b32_e32 v224, 16, v194
	v_and_b32_e32 v225, 0xffff0000, v194
	v_lshlrev_b32_e32 v226, 16, v198
	v_and_b32_e32 v227, 0xffff0000, v198
	v_fmac_f32_e32 v224, v88, v226
	v_fmac_f32_e32 v225, v89, v227
	v_cvt_pk_bf16_f32 v194, v224, v225
	v_lshlrev_b32_e32 v228, 16, v195
	v_and_b32_e32 v229, 0xffff0000, v195
	v_lshlrev_b32_e32 v230, 16, v199
	v_and_b32_e32 v231, 0xffff0000, v199
	v_fmac_f32_e32 v228, v90, v230
	v_fmac_f32_e32 v229, v91, v231
	v_cvt_pk_bf16_f32 v195, v228, v229
	v_lshlrev_b32_e32 v224, 16, v200
	v_and_b32_e32 v225, 0xffff0000, v200
	v_lshlrev_b32_e32 v226, 16, v204
	v_and_b32_e32 v227, 0xffff0000, v204
	v_fmac_f32_e32 v224, v84, v226
	v_fmac_f32_e32 v225, v85, v227
	v_cvt_pk_bf16_f32 v200, v224, v225
	v_lshlrev_b32_e32 v228, 16, v201
	v_and_b32_e32 v229, 0xffff0000, v201
	v_lshlrev_b32_e32 v230, 16, v205
	v_and_b32_e32 v231, 0xffff0000, v205
	v_fmac_f32_e32 v228, v86, v230
	v_fmac_f32_e32 v229, v87, v231
	v_cvt_pk_bf16_f32 v201, v228, v229
	v_lshlrev_b32_e32 v224, 16, v202
	v_and_b32_e32 v225, 0xffff0000, v202
	v_lshlrev_b32_e32 v226, 16, v206
	v_and_b32_e32 v227, 0xffff0000, v206
	v_fmac_f32_e32 v224, v80, v226
	v_fmac_f32_e32 v225, v81, v227
	v_cvt_pk_bf16_f32 v202, v224, v225
	v_lshlrev_b32_e32 v228, 16, v203
	v_and_b32_e32 v229, 0xffff0000, v203
	v_lshlrev_b32_e32 v230, 16, v207
	v_and_b32_e32 v231, 0xffff0000, v207
	v_fmac_f32_e32 v228, v82, v230
	v_fmac_f32_e32 v229, v83, v231
	v_cvt_pk_bf16_f32 v203, v228, v229
	v_lshlrev_b32_e32 v224, 16, v208
	v_and_b32_e32 v225, 0xffff0000, v208
	v_lshlrev_b32_e32 v226, 16, v212
	v_and_b32_e32 v227, 0xffff0000, v212
	v_fmac_f32_e32 v224, v76, v226
	v_fmac_f32_e32 v225, v77, v227
	v_cvt_pk_bf16_f32 v208, v224, v225
	v_lshlrev_b32_e32 v228, 16, v209
	v_and_b32_e32 v229, 0xffff0000, v209
	v_lshlrev_b32_e32 v230, 16, v213
	v_and_b32_e32 v231, 0xffff0000, v213
	v_fmac_f32_e32 v228, v78, v230
	v_fmac_f32_e32 v229, v79, v231
	v_cvt_pk_bf16_f32 v209, v228, v229
	v_lshlrev_b32_e32 v224, 16, v210
	v_and_b32_e32 v225, 0xffff0000, v210
	v_lshlrev_b32_e32 v226, 16, v214
	v_and_b32_e32 v227, 0xffff0000, v214
	v_fmac_f32_e32 v224, v72, v226
	v_fmac_f32_e32 v225, v73, v227
	v_cvt_pk_bf16_f32 v210, v224, v225
	v_lshlrev_b32_e32 v228, 16, v211
	v_and_b32_e32 v229, 0xffff0000, v211
	v_lshlrev_b32_e32 v230, 16, v215
	v_and_b32_e32 v231, 0xffff0000, v215
	v_fmac_f32_e32 v228, v74, v230
	v_fmac_f32_e32 v229, v75, v231
	v_cvt_pk_bf16_f32 v211, v228, v229
	v_lshlrev_b32_e32 v224, 16, v216
	v_and_b32_e32 v225, 0xffff0000, v216
	v_lshlrev_b32_e32 v226, 16, v220
	v_and_b32_e32 v227, 0xffff0000, v220
	v_fmac_f32_e32 v224, v68, v226
	v_fmac_f32_e32 v225, v69, v227
	v_cvt_pk_bf16_f32 v216, v224, v225
	v_lshlrev_b32_e32 v228, 16, v217
	v_and_b32_e32 v229, 0xffff0000, v217
	v_lshlrev_b32_e32 v230, 16, v221
	v_and_b32_e32 v231, 0xffff0000, v221
	v_fmac_f32_e32 v228, v70, v230
	v_fmac_f32_e32 v229, v71, v231
	v_cvt_pk_bf16_f32 v217, v228, v229
	v_lshlrev_b32_e32 v224, 16, v218
	v_and_b32_e32 v225, 0xffff0000, v218
	v_lshlrev_b32_e32 v226, 16, v222
	v_and_b32_e32 v227, 0xffff0000, v222
	v_fmac_f32_e32 v224, v64, v226
	v_fmac_f32_e32 v225, v65, v227
	v_cvt_pk_bf16_f32 v218, v224, v225
	v_lshlrev_b32_e32 v228, 16, v219
	v_and_b32_e32 v229, 0xffff0000, v219
	v_lshlrev_b32_e32 v230, 16, v223
	v_and_b32_e32 v231, 0xffff0000, v223
	v_fmac_f32_e32 v228, v66, v230
	v_fmac_f32_e32 v229, v67, v231
	v_cvt_pk_bf16_f32 v219, v228, v229
	s_sub_u32 s98, s98, 0x30000
	s_subb_u32 s99, s99, 0
	s_sub_u32 s100, s100, 0x30000
	s_subb_u32 s101, s101, 0
	global_store_dwordx4 v144, v[160:163], s[98:99]
	global_store_dwordx4 v144, v[168:171], s[98:99] offset:256
	s_add_u32 s98, s98, 0x10000
	s_addc_u32 s99, s99, 0
	s_add_u32 s100, s100, 0x10000
	s_addc_u32 s101, s101, 0
	global_store_dwordx4 v144, v[176:179], s[98:99]
	global_store_dwordx4 v144, v[184:187], s[98:99] offset:256
	s_add_u32 s98, s98, 0x10000
	s_addc_u32 s99, s99, 0
	s_add_u32 s100, s100, 0x10000
	s_addc_u32 s101, s101, 0
	global_store_dwordx4 v144, v[192:195], s[98:99]
	global_store_dwordx4 v144, v[200:203], s[98:99] offset:256
	s_add_u32 s98, s98, 0x10000
	s_addc_u32 s99, s99, 0
	s_add_u32 s100, s100, 0x10000
	s_addc_u32 s101, s101, 0
	global_store_dwordx4 v144, v[208:211], s[98:99]
	global_store_dwordx4 v144, v[216:219], s[98:99] offset:256
	s_add_u32 s98, s98, 0x50000
	s_addc_u32 s99, s99, 0
	s_add_u32 s100, s100, 0x50000
	s_addc_u32 s101, s101, 0
	global_load_dwordx4 v[160:163], v144, s[98:99]
	global_load_dwordx4 v[164:167], v144, s[100:101]
	global_load_dwordx4 v[168:171], v144, s[98:99] offset:256
	global_load_dwordx4 v[172:175], v144, s[100:101] offset:256
	s_add_u32 s98, s98, 0x10000
	s_addc_u32 s99, s99, 0
	s_add_u32 s100, s100, 0x10000
	s_addc_u32 s101, s101, 0
	global_load_dwordx4 v[176:179], v144, s[98:99]
	global_load_dwordx4 v[180:183], v144, s[100:101]
	global_load_dwordx4 v[184:187], v144, s[98:99] offset:256
	global_load_dwordx4 v[188:191], v144, s[100:101] offset:256
	s_add_u32 s98, s98, 0x10000
	s_addc_u32 s99, s99, 0
	s_add_u32 s100, s100, 0x10000
	s_addc_u32 s101, s101, 0
	global_load_dwordx4 v[192:195], v144, s[98:99]
	global_load_dwordx4 v[196:199], v144, s[100:101]
	global_load_dwordx4 v[200:203], v144, s[98:99] offset:256
	global_load_dwordx4 v[204:207], v144, s[100:101] offset:256
	s_add_u32 s98, s98, 0x10000
	s_addc_u32 s99, s99, 0
	s_add_u32 s100, s100, 0x10000
	s_addc_u32 s101, s101, 0
	global_load_dwordx4 v[208:211], v144, s[98:99]
	global_load_dwordx4 v[212:215], v144, s[100:101]
	global_load_dwordx4 v[216:219], v144, s[98:99] offset:256
	global_load_dwordx4 v[220:223], v144, s[100:101] offset:256
	s_waitcnt vmcnt(0)
; __device__ __forceinline__ float bf_lo(unsigned w) { return __uint_as_float(w << 16); }
; __device__ __forceinline__ float bf_hi(unsigned w) { return __uint_as_float(w & 0xffff0000u); }
; __device__ __forceinline__ u32x4 pack8(f32x4 a, f32x4 b) { u32x4 w; w.x = cvt_pk_bf16(a[0], a[1]); w.y = cvt_pk_bf16(a[2], a[3]); w.z = cvt_pk_bf16(b[0], b[1]); w.w = cvt_pk_bf16(b[2], b[3]); return w; }
;     __device__ __forceinline__ void operator()(const f32x4 (&acc)[2][2][4][2], const Unit& u, int wr, int wc, int fr, int fq) const {
;         const int row0 = u.pm * BM + wr * 64 + fr, c0 = u.pn * BM + wc * 32 + 8 * fq;
; #pragma unroll
;         for (int ai = 0; ai < 2; ++ai)
; #pragma unroll
;             for (int m = 0; m < 4; ++m) { const size_t off = (size_t)(row0 + ai * HALF + m * 16) * 2048 + c0;
; #pragma unroll
;                 for (int bj = 0; bj < 2; ++bj) { const u32x4 t = *(const u32x4*)(T + off + bj * HALF); const u32x4 g = *(const u32x4*)(G + off + bj * HALF);
;                     const f32x4 v0 = acc[ai][bj][m][0], v1 = acc[ai][bj][m][1];
;                     const f32x4 o0 = {bf_lo(t.x) + bf_lo(g.x) * v0[0], bf_hi(t.x) + bf_hi(g.x) * v0[1], bf_lo(t.y) + bf_lo(g.y) * v0[2], bf_hi(t.y) + bf_hi(g.y) * v0[3]};
;                     const f32x4 o1 = {bf_lo(t.z) + bf_lo(g.z) * v1[0], bf_hi(t.z) + bf_hi(g.z) * v1[1], bf_lo(t.w) + bf_lo(g.w) * v1[2], bf_hi(t.w) + bf_hi(g.w) * v1[3]};
;                     *(u32x4*)(T + off + bj * HALF) = pack8(o0, o1); } }
	v_lshlrev_b32_e32 v224, 16, v160
	v_and_b32_e32 v225, 0xffff0000, v160
	v_lshlrev_b32_e32 v226, 16, v164
	v_and_b32_e32 v227, 0xffff0000, v164
	v_fmac_f32_e32 v224, v60, v226
	v_fmac_f32_e32 v225, v61, v227
	v_cvt_pk_bf16_f32 v160, v224, v225
	v_lshlrev_b32_e32 v228, 16, v161
	v_and_b32_e32 v229, 0xffff0000, v161
	v_lshlrev_b32_e32 v230, 16, v165
	v_and_b32_e32 v231, 0xffff0000, v165
	v_fmac_f32_e32 v228, v62, v230
	v_fmac_f32_e32 v229, v63, v231
	v_cvt_pk_bf16_f32 v161, v228, v229
	v_lshlrev_b32_e32 v224, 16, v162
	v_and_b32_e32 v225, 0xffff0000, v162
	v_lshlrev_b32_e32 v226, 16, v166
	v_and_b32_e32 v227, 0xffff0000, v166
	v_fmac_f32_e32 v224, v56, v226
	v_fmac_f32_e32 v225, v57, v227
	v_cvt_pk_bf16_f32 v162, v224, v225
	v_lshlrev_b32_e32 v228, 16, v163
	v_and_b32_e32 v229, 0xffff0000, v163
	v_lshlrev_b32_e32 v230, 16, v167
	v_and_b32_e32 v231, 0xffff0000, v167
	v_fmac_f32_e32 v228, v58, v230
	v_fmac_f32_e32 v229, v59, v231
	v_cvt_pk_bf16_f32 v163, v228, v229
	v_lshlrev_b32_e32 v224, 16, v168
	v_and_b32_e32 v225, 0xffff0000, v168
	v_lshlrev_b32_e32 v226, 16, v172
	v_and_b32_e32 v227, 0xffff0000, v172
	v_fmac_f32_e32 v224, v52, v226
	v_fmac_f32_e32 v225, v53, v227
	v_cvt_pk_bf16_f32 v168, v224, v225
	v_lshlrev_b32_e32 v228, 16, v169
	v_and_b32_e32 v229, 0xffff0000, v169
	v_lshlrev_b32_e32 v230, 16, v173
	v_and_b32_e32 v231, 0xffff0000, v173
	v_fmac_f32_e32 v228, v54, v230
	v_fmac_f32_e32 v229, v55, v231
	v_cvt_pk_bf16_f32 v169, v228, v229
	v_lshlrev_b32_e32 v224, 16, v170
	v_and_b32_e32 v225, 0xffff0000, v170
	v_lshlrev_b32_e32 v226, 16, v174
	v_and_b32_e32 v227, 0xffff0000, v174
	v_fmac_f32_e32 v224, v48, v226
	v_fmac_f32_e32 v225, v49, v227
	v_cvt_pk_bf16_f32 v170, v224, v225
	v_lshlrev_b32_e32 v228, 16, v171
	v_and_b32_e32 v229, 0xffff0000, v171
	v_lshlrev_b32_e32 v230, 16, v175
	v_and_b32_e32 v231, 0xffff0000, v175
	v_fmac_f32_e32 v228, v50, v230
	v_fmac_f32_e32 v229, v51, v231
	v_cvt_pk_bf16_f32 v171, v228, v229
	v_lshlrev_b32_e32 v224, 16, v176
	v_and_b32_e32 v225, 0xffff0000, v176
	v_lshlrev_b32_e32 v226, 16, v180
	v_and_b32_e32 v227, 0xffff0000, v180
	v_fmac_f32_e32 v224, v44, v226
	v_fmac_f32_e32 v225, v45, v227
	v_cvt_pk_bf16_f32 v176, v224, v225
	v_lshlrev_b32_e32 v228, 16, v177
	v_and_b32_e32 v229, 0xffff0000, v177
	v_lshlrev_b32_e32 v230, 16, v181
	v_and_b32_e32 v231, 0xffff0000, v181
	v_fmac_f32_e32 v228, v46, v230
	v_fmac_f32_e32 v229, v47, v231
	v_cvt_pk_bf16_f32 v177, v228, v229
	v_lshlrev_b32_e32 v224, 16, v178
	v_and_b32_e32 v225, 0xffff0000, v178
	v_lshlrev_b32_e32 v226, 16, v182
	v_and_b32_e32 v227, 0xffff0000, v182
	v_fmac_f32_e32 v224, v40, v226
	v_fmac_f32_e32 v225, v41, v227
	v_cvt_pk_bf16_f32 v178, v224, v225
	v_lshlrev_b32_e32 v228, 16, v179
	v_and_b32_e32 v229, 0xffff0000, v179
	v_lshlrev_b32_e32 v230, 16, v183
	v_and_b32_e32 v231, 0xffff0000, v183
	v_fmac_f32_e32 v228, v42, v230
	v_fmac_f32_e32 v229, v43, v231
	v_cvt_pk_bf16_f32 v179, v228, v229
	v_lshlrev_b32_e32 v224, 16, v184
	v_and_b32_e32 v225, 0xffff0000, v184
	v_lshlrev_b32_e32 v226, 16, v188
	v_and_b32_e32 v227, 0xffff0000, v188
	v_fmac_f32_e32 v224, v36, v226
	v_fmac_f32_e32 v225, v37, v227
	v_cvt_pk_bf16_f32 v184, v224, v225
	v_lshlrev_b32_e32 v228, 16, v185
	v_and_b32_e32 v229, 0xffff0000, v185
	v_lshlrev_b32_e32 v230, 16, v189
	v_and_b32_e32 v231, 0xffff0000, v189
	v_fmac_f32_e32 v228, v38, v230
	v_fmac_f32_e32 v229, v39, v231
	v_cvt_pk_bf16_f32 v185, v228, v229
	v_lshlrev_b32_e32 v224, 16, v186
	v_and_b32_e32 v225, 0xffff0000, v186
	v_lshlrev_b32_e32 v226, 16, v190
	v_and_b32_e32 v227, 0xffff0000, v190
	v_fmac_f32_e32 v224, v32, v226
	v_fmac_f32_e32 v225, v33, v227
	v_cvt_pk_bf16_f32 v186, v224, v225
	v_lshlrev_b32_e32 v228, 16, v187
	v_and_b32_e32 v229, 0xffff0000, v187
	v_lshlrev_b32_e32 v230, 16, v191
	v_and_b32_e32 v231, 0xffff0000, v191
	v_fmac_f32_e32 v228, v34, v230
	v_fmac_f32_e32 v229, v35, v231
	v_cvt_pk_bf16_f32 v187, v228, v229
	v_lshlrev_b32_e32 v224, 16, v192
	v_and_b32_e32 v225, 0xffff0000, v192
	v_lshlrev_b32_e32 v226, 16, v196
	v_and_b32_e32 v227, 0xffff0000, v196
	v_fmac_f32_e32 v224, v28, v226
	v_fmac_f32_e32 v225, v29, v227
	v_cvt_pk_bf16_f32 v192, v224, v225
	v_lshlrev_b32_e32 v228, 16, v193
	v_and_b32_e32 v229, 0xffff0000, v193
	v_lshlrev_b32_e32 v230, 16, v197
	v_and_b32_e32 v231, 0xffff0000, v197
	v_fmac_f32_e32 v228, v30, v230
	v_fmac_f32_e32 v229, v31, v231
	v_cvt_pk_bf16_f32 v193, v228, v229
; __device__ __forceinline__ float bf_lo(unsigned w) { return __uint_as_float(w << 16); }
; __device__ __forceinline__ float bf_hi(unsigned w) { return __uint_as_float(w & 0xffff0000u); }
; __device__ __forceinline__ u32x4 pack8(f32x4 a, f32x4 b) { u32x4 w; w.x = cvt_pk_bf16(a[0], a[1]); w.y = cvt_pk_bf16(a[2], a[3]); w.z = cvt_pk_bf16(b[0], b[1]); w.w = cvt_pk_bf16(b[2], b[3]); return w; }
;     __device__ __forceinline__ void operator()(const f32x4 (&acc)[2][2][4][2], const Unit& u, int wr, int wc, int fr, int fq) const {
;         const int row0 = u.pm * BM + wr * 64 + fr, c0 = u.pn * BM + wc * 32 + 8 * fq;
; #pragma unroll
;         for (int ai = 0; ai < 2; ++ai)
; #pragma unroll
;             for (int m = 0; m < 4; ++m) { const size_t off = (size_t)(row0 + ai * HALF + m * 16) * 2048 + c0;
; #pragma unroll
;                 for (int bj = 0; bj < 2; ++bj) { const u32x4 t = *(const u32x4*)(T + off + bj * HALF); const u32x4 g = *(const u32x4*)(G + off + bj * HALF);
;                     const f32x4 v0 = acc[ai][bj][m][0], v1 = acc[ai][bj][m][1];
;                     const f32x4 o0 = {bf_lo(t.x) + bf_lo(g.x) * v0[0], bf_hi(t.x) + bf_hi(g.x) * v0[1], bf_lo(t.y) + bf_lo(g.y) * v0[2], bf_hi(t.y) + bf_hi(g.y) * v0[3]};
;                     const f32x4 o1 = {bf_lo(t.z) + bf_lo(g.z) * v1[0], bf_hi(t.z) + bf_hi(g.z) * v1[1], bf_lo(t.w) + bf_lo(g.w) * v1[2], bf_hi(t.w) + bf_hi(g.w) * v1[3]};
;                     *(u32x4*)(T + off + bj * HALF) = pack8(o0, o1); } }
	v_lshlrev_b32_e32 v224, 16, v194
	v_and_b32_e32 v225, 0xffff0000, v194
	v_lshlrev_b32_e32 v226, 16, v198
	v_and_b32_e32 v227, 0xffff0000, v198
	v_fmac_f32_e32 v224, v24, v226
	v_fmac_f32_e32 v225, v25, v227
	v_cvt_pk_bf16_f32 v194, v224, v225
	v_lshlrev_b32_e32 v228, 16, v195
	v_and_b32_e32 v229, 0xffff0000, v195
	v_lshlrev_b32_e32 v230, 16, v199
	v_and_b32_e32 v231, 0xffff0000, v199
	v_fmac_f32_e32 v228, v26, v230
	v_fmac_f32_e32 v229, v27, v231
	v_cvt_pk_bf16_f32 v195, v228, v229
	v_lshlrev_b32_e32 v224, 16, v200
	v_and_b32_e32 v225, 0xffff0000, v200
	v_lshlrev_b32_e32 v226, 16, v204
	v_and_b32_e32 v227, 0xffff0000, v204
	v_fmac_f32_e32 v224, v20, v226
	v_fmac_f32_e32 v225, v21, v227
	v_cvt_pk_bf16_f32 v200, v224, v225
	v_lshlrev_b32_e32 v228, 16, v201
	v_and_b32_e32 v229, 0xffff0000, v201
	v_lshlrev_b32_e32 v230, 16, v205
	v_and_b32_e32 v231, 0xffff0000, v205
	v_fmac_f32_e32 v228, v22, v230
	v_fmac_f32_e32 v229, v23, v231
	v_cvt_pk_bf16_f32 v201, v228, v229
	v_lshlrev_b32_e32 v224, 16, v202
	v_and_b32_e32 v225, 0xffff0000, v202
	v_lshlrev_b32_e32 v226, 16, v206
	v_and_b32_e32 v227, 0xffff0000, v206
	v_fmac_f32_e32 v224, v16, v226
	v_fmac_f32_e32 v225, v17, v227
	v_cvt_pk_bf16_f32 v202, v224, v225
	v_lshlrev_b32_e32 v228, 16, v203
	v_and_b32_e32 v229, 0xffff0000, v203
	v_lshlrev_b32_e32 v230, 16, v207
	v_and_b32_e32 v231, 0xffff0000, v207
	v_fmac_f32_e32 v228, v18, v230
	v_fmac_f32_e32 v229, v19, v231
	v_cvt_pk_bf16_f32 v203, v228, v229
	v_lshlrev_b32_e32 v224, 16, v208
	v_and_b32_e32 v225, 0xffff0000, v208
	v_lshlrev_b32_e32 v226, 16, v212
	v_and_b32_e32 v227, 0xffff0000, v212
	v_fmac_f32_e32 v224, v12, v226
	v_fmac_f32_e32 v225, v13, v227
	v_cvt_pk_bf16_f32 v208, v224, v225
	v_lshlrev_b32_e32 v228, 16, v209
	v_and_b32_e32 v229, 0xffff0000, v209
	v_lshlrev_b32_e32 v230, 16, v213
	v_and_b32_e32 v231, 0xffff0000, v213
	v_fmac_f32_e32 v228, v14, v230
	v_fmac_f32_e32 v229, v15, v231
	v_cvt_pk_bf16_f32 v209, v228, v229
	v_lshlrev_b32_e32 v224, 16, v210
	v_and_b32_e32 v225, 0xffff0000, v210
	v_lshlrev_b32_e32 v226, 16, v214
	v_and_b32_e32 v227, 0xffff0000, v214
	v_fmac_f32_e32 v224, v8, v226
	v_fmac_f32_e32 v225, v9, v227
	v_cvt_pk_bf16_f32 v210, v224, v225
	v_lshlrev_b32_e32 v228, 16, v211
	v_and_b32_e32 v229, 0xffff0000, v211
	v_lshlrev_b32_e32 v230, 16, v215
	v_and_b32_e32 v231, 0xffff0000, v215
	v_fmac_f32_e32 v228, v10, v230
	v_fmac_f32_e32 v229, v11, v231
	v_cvt_pk_bf16_f32 v211, v228, v229
	v_lshlrev_b32_e32 v224, 16, v216
	v_and_b32_e32 v225, 0xffff0000, v216
	v_lshlrev_b32_e32 v226, 16, v220
	v_and_b32_e32 v227, 0xffff0000, v220
	v_fmac_f32_e32 v224, v4, v226
	v_fmac_f32_e32 v225, v5, v227
	v_cvt_pk_bf16_f32 v216, v224, v225
	v_lshlrev_b32_e32 v228, 16, v217
	v_and_b32_e32 v229, 0xffff0000, v217
	v_lshlrev_b32_e32 v230, 16, v221
	v_and_b32_e32 v231, 0xffff0000, v221
	v_fmac_f32_e32 v228, v6, v230
	v_fmac_f32_e32 v229, v7, v231
	v_cvt_pk_bf16_f32 v217, v228, v229
	v_lshlrev_b32_e32 v224, 16, v218
	v_and_b32_e32 v225, 0xffff0000, v218
	v_lshlrev_b32_e32 v226, 16, v222
	v_and_b32_e32 v227, 0xffff0000, v222
	v_fmac_f32_e32 v224, v0, v226
	v_fmac_f32_e32 v225, v1, v227
	v_cvt_pk_bf16_f32 v218, v224, v225
	v_lshlrev_b32_e32 v228, 16, v219
	v_and_b32_e32 v229, 0xffff0000, v219
	v_lshlrev_b32_e32 v230, 16, v223
	v_and_b32_e32 v231, 0xffff0000, v223
	v_fmac_f32_e32 v228, v2, v230
	v_fmac_f32_e32 v229, v3, v231
	v_cvt_pk_bf16_f32 v219, v228, v229
	s_sub_u32 s98, s98, 0x30000
	s_subb_u32 s99, s99, 0
	s_sub_u32 s100, s100, 0x30000
	s_subb_u32 s101, s101, 0
	global_store_dwordx4 v144, v[160:163], s[98:99]
	global_store_dwordx4 v144, v[168:171], s[98:99] offset:256
	s_add_u32 s98, s98, 0x10000
	s_addc_u32 s99, s99, 0
	s_add_u32 s100, s100, 0x10000
	s_addc_u32 s101, s101, 0
	global_store_dwordx4 v144, v[176:179], s[98:99]
	global_store_dwordx4 v144, v[184:187], s[98:99] offset:256
	s_add_u32 s98, s98, 0x10000
	s_addc_u32 s99, s99, 0
	s_add_u32 s100, s100, 0x10000
	s_addc_u32 s101, s101, 0
	global_store_dwordx4 v144, v[192:195], s[98:99]
	global_store_dwordx4 v144, v[200:203], s[98:99] offset:256
	s_add_u32 s98, s98, 0x10000
	s_addc_u32 s99, s99, 0
	s_add_u32 s100, s100, 0x10000
	s_addc_u32 s101, s101, 0
	global_store_dwordx4 v144, v[208:211], s[98:99]
	global_store_dwordx4 v144, v[216:219], s[98:99] offset:256
	s_cbranch_vccnz .LBB0_749
	s_andn2_b64 vcc, exec, s[8:9]
	s_cbranch_vccnz .LBB0_748
	s_barrier
	s_branch .LBB0_748
